# fused rmsnorm epilogues: the 16 cross-workgroup partial-sum loads issued as one batch instead of 8 dependent round trips
# speedup vs baseline: 1.0006x; 1.0006x over previous
;     __device__ __forceinline__ void fused(f32x4 (&acc)[2][2][4][2], const Unit& u, int wr, int wc, int fr, int fq, PG8_LAS unsigned char* lds, int wid, int lane) const {
;     ...
;         if (lane < 32) { float saa = 0.f, sxx = 0.f, sxag = 0.f, sgg = 0.f;
; #pragma unroll
;             for (int t = 0; t < 8; ++t) { const unsigned long long w0 = __hip_atomic_load(slot + t * 2, __ATOMIC_RELAXED, __HIP_MEMORY_SCOPE_AGENT), w1 = __hip_atomic_load(slot + t * 2 + 1, __ATOMIC_RELAXED, __HIP_MEMORY_SCOPE_AGENT);
;                 saa += __uint_as_float((unsigned)w0); sxx += __uint_as_float((unsigned)(w0 >> 32)); sxag += __uint_as_float((unsigned)w1); sgg += __uint_as_float((unsigned)(w1 >> 32)); }
;             const float r1 = 1.0f / sqrtf(saa * inv_n + eps);
;             float s1 = sxx + 2.0f * r1 * sxag + r1 * r1 * sgg; s1 = s1 < 0.f ? 0.f : s1;
;             S[row * 2] = r1; S[row * 2 + 1] = 1.0f / sqrtf(s1 * inv_n + eps); }
.LBB0_862:
	s_waitcnt vmcnt(0) lgkmcnt(0)
	s_barrier
	s_and_saveexec_b64 s[4:5], s[0:1]
	s_cbranch_execz .LBB0_864
	s_waitcnt lgkmcnt(0)
	global_load_dwordx2 v[224:225], v[130:131], off sc1
	global_load_dwordx2 v[132:133], v[130:131], off offset:8 sc1
	global_load_dwordx2 v[226:227], v[130:131], off offset:16 sc1
	global_load_dwordx2 v[134:135], v[130:131], off offset:24 sc1
	global_load_dwordx2 v[228:229], v[130:131], off offset:32 sc1
	global_load_dwordx2 v[136:137], v[130:131], off offset:40 sc1
	global_load_dwordx2 v[230:231], v[130:131], off offset:48 sc1
	global_load_dwordx2 v[142:143], v[130:131], off offset:56 sc1
	global_load_dwordx2 v[232:233], v[130:131], off offset:64 sc1
	global_load_dwordx2 v[144:145], v[130:131], off offset:72 sc1
	global_load_dwordx2 v[234:235], v[130:131], off offset:80 sc1
	global_load_dwordx2 v[146:147], v[130:131], off offset:88 sc1
	global_load_dwordx2 v[236:237], v[130:131], off offset:96 sc1
	global_load_dwordx2 v[148:149], v[130:131], off offset:104 sc1
	global_load_dwordx2 v[238:239], v[130:131], off offset:112 sc1
	s_nop 0
	global_load_dwordx2 v[130:131], v[130:131], off offset:120 sc1
	s_mov_b32 s6, 0xf800000
	s_waitcnt vmcnt(0)
	v_add_f32_e32 v139, 0, v224
	v_add_f32_e32 v150, 0, v225
	v_add_f32_e32 v139, v139, v226
	v_add_f32_e32 v150, v150, v227
	v_add_f32_e32 v139, v139, v228
	v_add_f32_e32 v150, v150, v229
	v_add_f32_e32 v139, v139, v230
	v_add_f32_e32 v150, v150, v231
	v_add_f32_e32 v139, v139, v232
	v_add_f32_e32 v150, v150, v233
	v_add_f32_e32 v139, v139, v234
	v_add_f32_e32 v150, v150, v235
	v_add_f32_e32 v139, v139, v236
	v_add_f32_e32 v150, v150, v237
	v_add_f32_e32 v139, v139, v238
	v_add_f32_e32 v150, v150, v239
	v_fmamk_f32 v139, v139, 0x3a000000, v189
	v_cmp_gt_f32_e32 vcc, s6, v139
	v_mul_f32_e32 v140, 0x4f800000, v139
	v_cndmask_b32_e32 v139, v139, v140, vcc
	v_sqrt_f32_e32 v140, v139
	s_nop 0
	v_add_u32_e32 v141, -1, v140
	v_fma_f32 v151, -v141, v140, v139
	v_cmp_ge_f32_e64 s[0:1], 0, v151
	v_add_u32_e32 v151, 1, v140
	s_nop 0
	v_cndmask_b32_e64 v141, v140, v141, s[0:1]
	v_fma_f32 v140, -v151, v140, v139
	v_cmp_lt_f32_e64 s[0:1], 0, v140
	s_nop 1
	v_cndmask_b32_e64 v140, v141, v151, s[0:1]
	v_mul_f32_e32 v141, 0x37800000, v140
	v_cndmask_b32_e32 v140, v140, v141, vcc
	v_cmp_class_f32_e32 vcc, v139, v190
	s_nop 1
	v_cndmask_b32_e32 v139, v140, v139, vcc
	v_div_scale_f32 v140, s[0:1], v139, v139, 1.0
	v_rcp_f32_e32 v141, v140
	s_nop 0
	v_fma_f32 v151, -v140, v141, 1.0
	v_fmac_f32_e32 v141, v151, v141
	v_div_scale_f32 v151, vcc, 1.0, v139, 1.0
	v_mul_f32_e32 v152, v151, v141
	v_fma_f32 v153, -v140, v152, v151
	v_fmac_f32_e32 v152, v153, v141
	v_fma_f32 v140, -v140, v152, v151
	v_div_fmas_f32 v140, v140, v141, v152
	v_div_fixup_f32 v162, v140, v139, 1.0
	v_mov_b32_e32 v140, v133
	v_mov_b32_e32 v141, v132
	v_pk_add_f32 v[132:133], v[140:141], 0 op_sel_hi:[1,0]
	v_mov_b32_e32 v140, v135
	v_mov_b32_e32 v141, v134
	v_pk_add_f32 v[132:133], v[132:133], v[140:141]
	v_mov_b32_e32 v134, v137
	v_mov_b32_e32 v135, v136
	v_pk_add_f32 v[132:133], v[132:133], v[134:135]
	v_mov_b32_e32 v134, v143
	v_mov_b32_e32 v135, v142
	v_pk_add_f32 v[132:133], v[132:133], v[134:135]
	v_mov_b32_e32 v134, v145
	v_mov_b32_e32 v135, v144
	v_pk_add_f32 v[132:133], v[132:133], v[134:135]
	v_mov_b32_e32 v134, v147
	v_mov_b32_e32 v135, v146
	v_pk_add_f32 v[132:133], v[132:133], v[134:135]
	v_mov_b32_e32 v134, v149
	v_mov_b32_e32 v135, v148
	v_pk_add_f32 v[132:133], v[132:133], v[134:135]
	s_waitcnt vmcnt(0)
	v_mov_b32_e32 v134, v131
	v_mov_b32_e32 v135, v130
	v_pk_add_f32 v[130:131], v[132:133], v[134:135]
	v_pk_mul_f32 v[132:133], v[162:163], v[162:163] op_sel_hi:[0,1]
	v_pk_mul_f32 v[130:131], v[130:131], v[132:133]
	s_nop 0
	v_add_f32_e32 v131, v150, v131
	v_add_f32_e32 v130, v130, v131
	v_cmp_ngt_f32_e32 vcc, 0, v130
	v_lshl_add_u32 v131, v138, 3, 0
	v_add_u32_e32 v132, 0x24000, v131
	v_cndmask_b32_e32 v130, 0, v130, vcc
	v_fmamk_f32 v130, v130, 0x3a000000, v189
	v_cmp_gt_f32_e32 vcc, s6, v130
	v_mul_f32_e32 v131, 0x4f800000, v130
	s_nop 0
	v_cndmask_b32_e32 v130, v130, v131, vcc
	v_sqrt_f32_e32 v131, v130
	s_nop 0
	v_add_u32_e32 v133, -1, v131
	v_fma_f32 v134, -v133, v131, v130
	v_cmp_ge_f32_e64 s[0:1], 0, v134
	v_add_u32_e32 v134, 1, v131
	s_nop 0
	v_cndmask_b32_e64 v133, v131, v133, s[0:1]
	v_fma_f32 v131, -v134, v131, v130
	v_cmp_lt_f32_e64 s[0:1], 0, v131
	s_nop 1
	v_cndmask_b32_e64 v131, v133, v134, s[0:1]
	v_mul_f32_e32 v133, 0x37800000, v131
	v_cndmask_b32_e32 v131, v131, v133, vcc
	v_cmp_class_f32_e32 vcc, v130, v190
	s_nop 1
	v_cndmask_b32_e32 v130, v131, v130, vcc
	v_div_scale_f32 v131, s[0:1], v130, v130, 1.0
	v_rcp_f32_e32 v133, v131
	s_nop 0
	v_fma_f32 v134, -v131, v133, 1.0
	v_fmac_f32_e32 v133, v134, v133
	v_div_scale_f32 v134, vcc, 1.0, v130, 1.0
	v_mul_f32_e32 v135, v134, v133
	v_fma_f32 v136, -v131, v135, v134
	v_fmac_f32_e32 v135, v136, v133
	v_fma_f32 v131, -v131, v135, v134
	v_div_fmas_f32 v131, v131, v133, v135
	v_div_fixup_f32 v131, v131, v130, 1.0
	v_mov_b32_e32 v130, v162
	ds_write_b64 v132, v[130:131]
